# EpiRes (out-projection / FFN-out epilogue): second half's residual rows loaded together with the first half's into K-loop temporaries
# speedup vs baseline: 1.0089x; 1.0031x over previous
.LBB0_377:
	v_lshl_add_u32 v178, s29, 8, v171
	v_lshl_or_b32 v182, s27, 8, v197
	v_ashrrev_i32_e32 v183, 31, v182
	v_ashrrev_i32_e32 v179, 31, v178
	v_lshl_add_u64 v[180:181], v[182:183], 1, s[10:11]
	v_lshlrev_b64 v[122:123], 11, v[178:179]
	v_or_b32_e32 v188, 16, v178
	v_lshl_add_u64 v[122:123], v[180:181], 0, v[122:123]
	v_ashrrev_i32_e32 v189, 31, v188
	global_load_dwordx4 v[202:205], v[122:123], off
	global_load_dwordx4 v[158:161], v[122:123], off offset:256
	v_lshlrev_b64 v[122:123], 11, v[188:189]
	v_or_b32_e32 v186, 32, v178
	v_lshl_add_u64 v[122:123], v[180:181], 0, v[122:123]
	v_ashrrev_i32_e32 v187, 31, v186
	global_load_dwordx4 v[154:157], v[122:123], off
	global_load_dwordx4 v[150:153], v[122:123], off offset:256
	v_lshlrev_b64 v[122:123], 11, v[186:187]
	v_or_b32_e32 v184, 48, v178
	v_lshl_add_u64 v[122:123], v[180:181], 0, v[122:123]
	v_ashrrev_i32_e32 v185, 31, v184
	global_load_dwordx4 v[142:145], v[122:123], off
	global_load_dwordx4 v[138:141], v[122:123], off offset:256
	v_lshlrev_b64 v[122:123], 11, v[184:185]
	v_lshl_add_u64 v[122:123], v[180:181], 0, v[122:123]
	global_load_dwordx4 v[134:137], v[122:123], off
	s_nop 0
	global_load_dwordx4 v[122:125], v[122:123], off offset:256
	v_add_u32_e32 v238, 0x80, v178
	v_ashrrev_i32_e32 v239, 31, v238
	v_lshlrev_b64 v[238:239], 11, v[238:239]
	v_lshl_add_u64 v[238:239], v[180:181], 0, v[238:239]
	global_load_dwordx4 v[214:217], v[238:239], off
	global_load_dwordx4 v[218:221], v[238:239], off offset:256
	v_add_co_u32_e32 v238, vcc, 0x8000, v238
	s_nop 1
	v_addc_co_u32_e32 v239, vcc, 0, v239, vcc
	global_load_dwordx4 v[222:225], v[238:239], off
	global_load_dwordx4 v[226:229], v[238:239], off offset:256
	v_add_co_u32_e32 v238, vcc, 0x8000, v238
	s_nop 1
	v_addc_co_u32_e32 v239, vcc, 0, v239, vcc
	global_load_dwordx4 v[230:233], v[238:239], off
	global_load_dwordx4 v[234:237], v[238:239], off offset:256
	v_add_co_u32_e32 v238, vcc, 0x8000, v238
	s_nop 1
	v_addc_co_u32_e32 v239, vcc, 0, v239, vcc
	global_load_dwordx4 v[244:247], v[238:239], off
	global_load_dwordx4 v[248:251], v[238:239], off offset:256
	v_cndmask_b32_e64 v166, 0, 1, s[44:45]
	v_lshlrev_b64 v[194:195], 10, v[178:179]
	v_cmp_ne_u32_e64 s[40:41], 1, v166
	v_lshl_add_u64 v[190:191], v[194:195], 0, v[182:183]
	s_mov_b64 s[42:43], -1
	s_andn2_b64 vcc, exec, s[44:45]
	s_waitcnt vmcnt(8)
	v_lshlrev_b32_e32 v166, 16, v202
	v_and_b32_e32 v167, 0xffff0000, v202
	v_lshlrev_b32_e32 v192, 16, v203
	v_and_b32_e32 v193, 0xffff0000, v203
	v_lshlrev_b32_e32 v202, 16, v204
	v_and_b32_e32 v203, 0xffff0000, v204
	v_lshlrev_b32_e32 v204, 16, v205
	v_and_b32_e32 v205, 0xffff0000, v205
	v_pk_add_f32 v[132:133], v[132:133], v[192:193]
	v_pk_add_f32 v[130:131], v[130:131], v[166:167]
	v_pk_add_f32 v[128:129], v[128:129], v[204:205]
	v_pk_add_f32 v[126:127], v[126:127], v[202:203]
	v_lshl_add_u64 v[192:193], v[190:191], 2, s[8:9]
	s_cbranch_vccnz .LBB0_379
	s_mov_b64 s[42:43], 0
	global_store_dwordx4 v[192:193], v[130:133], off
	global_store_dwordx4 v[192:193], v[126:129], off offset:16

.LBB0_425:
	v_add_u32_e32 v100, 0x80, v178
	v_ashrrev_i32_e32 v101, 31, v100
	s_waitcnt lgkmcnt(0)
	v_lshlrev_b64 v[66:67], 11, v[100:101]
	v_add_u32_e32 v98, 0x90, v178
	v_lshl_add_u64 v[66:67], v[180:181], 0, v[66:67]
	v_ashrrev_i32_e32 v99, 31, v98
	v_lshlrev_b64 v[66:67], 11, v[98:99]
	v_add_u32_e32 v96, 0xa0, v178
	v_lshl_add_u64 v[66:67], v[180:181], 0, v[66:67]
	v_ashrrev_i32_e32 v97, 31, v96
	v_lshlrev_b64 v[66:67], 11, v[96:97]
	v_add_u32_e32 v94, 0xb0, v178
	v_lshl_add_u64 v[66:67], v[180:181], 0, v[66:67]
	v_ashrrev_i32_e32 v95, 31, v94
	v_lshlrev_b64 v[66:67], 11, v[94:95]
	v_lshl_add_u64 v[66:67], v[180:181], 0, v[66:67]
	s_nop 0
	v_lshlrev_b64 v[104:105], 10, v[100:101]
	v_lshl_add_u64 v[100:101], v[104:105], 0, v[182:183]
	s_mov_b64 s[48:49], -1
	s_and_b64 vcc, exec, s[40:41]
	s_waitcnt vmcnt(8)
	v_mov_b32_e32 v106, v214
	v_mov_b32_e32 v107, v215
	v_mov_b32_e32 v108, v216
	v_mov_b32_e32 v109, v217
	v_mov_b32_e32 v90, v218
	v_mov_b32_e32 v91, v219
	v_mov_b32_e32 v92, v220
	v_mov_b32_e32 v93, v221
	v_mov_b32_e32 v86, v222
	v_mov_b32_e32 v87, v223
	v_mov_b32_e32 v88, v224
	v_mov_b32_e32 v89, v225
	v_mov_b32_e32 v82, v226
	v_mov_b32_e32 v83, v227
	v_mov_b32_e32 v84, v228
	v_mov_b32_e32 v85, v229
	v_mov_b32_e32 v78, v230
	v_mov_b32_e32 v79, v231
	v_mov_b32_e32 v80, v232
	v_mov_b32_e32 v81, v233
	v_mov_b32_e32 v74, v234
	v_mov_b32_e32 v75, v235
	v_mov_b32_e32 v76, v236
	v_mov_b32_e32 v77, v237
	v_mov_b32_e32 v70, v244
	v_mov_b32_e32 v71, v245
	v_mov_b32_e32 v72, v246
	v_mov_b32_e32 v73, v247
	v_mov_b32_e32 v66, v248
	v_mov_b32_e32 v67, v249
	v_mov_b32_e32 v68, v250
	v_mov_b32_e32 v69, v251
	v_lshlrev_b32_e32 v102, 16, v106
	v_and_b32_e32 v103, 0xffff0000, v106
	v_lshlrev_b32_e32 v106, 16, v107
	v_and_b32_e32 v107, 0xffff0000, v107
	v_lshlrev_b32_e32 v110, 16, v108
	v_and_b32_e32 v111, 0xffff0000, v108
	v_lshlrev_b32_e32 v108, 16, v109
	v_and_b32_e32 v109, 0xffff0000, v109
	v_pk_add_f32 v[64:65], v[64:65], v[106:107]
	v_pk_add_f32 v[62:63], v[62:63], v[102:103]
	v_pk_add_f32 v[60:61], v[60:61], v[108:109]
	v_pk_add_f32 v[58:59], v[58:59], v[110:111]
	v_lshl_add_u64 v[102:103], v[100:101], 2, s[8:9]
	s_cbranch_vccnz .LBB0_427
	s_mov_b64 s[48:49], 0
	global_store_dwordx4 v[102:103], v[62:65], off
	global_store_dwordx4 v[102:103], v[58:61], off offset:16

.LBB0_429:
	v_lshlrev_b32_e32 v58, 16, v90
	v_and_b32_e32 v59, 0xffff0000, v90
	v_lshlrev_b32_e32 v60, 16, v91
	v_and_b32_e32 v61, 0xffff0000, v91
	v_lshlrev_b32_e32 v62, 16, v92
	v_and_b32_e32 v63, 0xffff0000, v92
	v_lshlrev_b32_e32 v64, 16, v93
	v_and_b32_e32 v65, 0xffff0000, v93
	v_pk_add_f32 v[56:57], v[56:57], v[60:61]
	v_pk_add_f32 v[54:55], v[54:55], v[58:59]
	v_pk_add_f32 v[52:53], v[52:53], v[64:65]
	v_pk_add_f32 v[50:51], v[50:51], v[62:63]
	s_and_b64 vcc, exec, s[40:41]
	s_mov_b64 s[48:49], -1
	s_cbranch_vccnz .LBB0_432
	global_store_dwordx4 v[102:103], v[54:57], off offset:512
	global_store_dwordx4 v[102:103], v[50:53], off offset:528
	s_cbranch_execz .LBB0_433

.LBB0_437:
	v_lshlrev_b64 v[54:55], 10, v[98:99]
	s_waitcnt lgkmcnt(0)
	v_lshl_add_u64 v[50:51], v[54:55], 0, v[182:183]
	v_lshlrev_b32_e32 v52, 16, v86
	v_and_b32_e32 v53, 0xffff0000, v86
	v_lshlrev_b32_e32 v56, 16, v87
	v_and_b32_e32 v57, 0xffff0000, v87
	v_lshlrev_b32_e32 v58, 16, v88
	v_and_b32_e32 v59, 0xffff0000, v88
	v_lshlrev_b32_e32 v60, 16, v89
	v_and_b32_e32 v61, 0xffff0000, v89
	v_pk_add_f32 v[48:49], v[48:49], v[56:57]
	v_pk_add_f32 v[46:47], v[46:47], v[52:53]
	v_pk_add_f32 v[44:45], v[44:45], v[60:61]
	v_pk_add_f32 v[42:43], v[42:43], v[58:59]
	s_mov_b64 s[48:49], -1
	s_and_b64 vcc, exec, s[40:41]
	v_lshl_add_u64 v[52:53], v[50:51], 2, s[8:9]
	s_cbranch_vccnz .LBB0_439
	s_mov_b64 s[48:49], 0
	global_store_dwordx4 v[52:53], v[46:49], off
	global_store_dwordx4 v[52:53], v[42:45], off offset:16

.LBB0_441:
	v_lshlrev_b32_e32 v42, 16, v82
	v_and_b32_e32 v43, 0xffff0000, v82
	v_lshlrev_b32_e32 v44, 16, v83
	v_and_b32_e32 v45, 0xffff0000, v83
	v_lshlrev_b32_e32 v46, 16, v84
	v_and_b32_e32 v47, 0xffff0000, v84
	v_lshlrev_b32_e32 v48, 16, v85
	v_and_b32_e32 v49, 0xffff0000, v85
	v_pk_add_f32 v[40:41], v[40:41], v[44:45]
	v_pk_add_f32 v[38:39], v[38:39], v[42:43]
	v_pk_add_f32 v[36:37], v[36:37], v[48:49]
	v_pk_add_f32 v[34:35], v[34:35], v[46:47]
	s_and_b64 vcc, exec, s[40:41]
	s_mov_b64 s[48:49], -1
	s_cbranch_vccnz .LBB0_444
	global_store_dwordx4 v[52:53], v[38:41], off offset:512
	global_store_dwordx4 v[52:53], v[34:37], off offset:528
	s_cbranch_execz .LBB0_445

.LBB0_449:
	v_lshlrev_b64 v[38:39], 10, v[96:97]
	s_waitcnt lgkmcnt(0)
	v_lshl_add_u64 v[34:35], v[38:39], 0, v[182:183]
	v_lshlrev_b32_e32 v36, 16, v78
	v_and_b32_e32 v37, 0xffff0000, v78
	v_lshlrev_b32_e32 v40, 16, v79
	v_and_b32_e32 v41, 0xffff0000, v79
	v_lshlrev_b32_e32 v42, 16, v80
	v_and_b32_e32 v43, 0xffff0000, v80
	v_lshlrev_b32_e32 v44, 16, v81
	v_and_b32_e32 v45, 0xffff0000, v81
	v_pk_add_f32 v[32:33], v[32:33], v[40:41]
	v_pk_add_f32 v[30:31], v[30:31], v[36:37]
	v_pk_add_f32 v[28:29], v[28:29], v[44:45]
	v_pk_add_f32 v[26:27], v[26:27], v[42:43]
	s_mov_b64 s[48:49], -1
	s_and_b64 vcc, exec, s[40:41]
	v_lshl_add_u64 v[36:37], v[34:35], 2, s[8:9]
	s_cbranch_vccnz .LBB0_451
	s_mov_b64 s[48:49], 0
	global_store_dwordx4 v[36:37], v[30:33], off
	global_store_dwordx4 v[36:37], v[26:29], off offset:16

.LBB0_453:
	v_lshlrev_b32_e32 v26, 16, v74
	v_and_b32_e32 v27, 0xffff0000, v74
	v_lshlrev_b32_e32 v28, 16, v75
	v_and_b32_e32 v29, 0xffff0000, v75
	v_lshlrev_b32_e32 v30, 16, v76
	v_and_b32_e32 v31, 0xffff0000, v76
	v_lshlrev_b32_e32 v32, 16, v77
	v_and_b32_e32 v33, 0xffff0000, v77
	v_pk_add_f32 v[24:25], v[24:25], v[28:29]
	v_pk_add_f32 v[22:23], v[22:23], v[26:27]
	v_pk_add_f32 v[20:21], v[20:21], v[32:33]
	v_pk_add_f32 v[18:19], v[18:19], v[30:31]
	s_and_b64 vcc, exec, s[40:41]
	s_mov_b64 s[48:49], -1
	s_cbranch_vccnz .LBB0_456
	global_store_dwordx4 v[36:37], v[22:25], off offset:512
	global_store_dwordx4 v[36:37], v[18:21], off offset:528
	s_cbranch_execz .LBB0_457

.LBB0_461:
	v_lshlrev_b64 v[22:23], 10, v[94:95]
	s_waitcnt lgkmcnt(0)
	v_lshl_add_u64 v[18:19], v[22:23], 0, v[182:183]
	v_lshlrev_b32_e32 v20, 16, v70
	v_and_b32_e32 v21, 0xffff0000, v70
	v_lshlrev_b32_e32 v24, 16, v71
	v_and_b32_e32 v25, 0xffff0000, v71
	v_lshlrev_b32_e32 v26, 16, v72
	v_and_b32_e32 v27, 0xffff0000, v72
	v_lshlrev_b32_e32 v28, 16, v73
	v_and_b32_e32 v29, 0xffff0000, v73
	v_pk_add_f32 v[16:17], v[16:17], v[24:25]
	v_pk_add_f32 v[14:15], v[14:15], v[20:21]
	v_pk_add_f32 v[12:13], v[12:13], v[28:29]
	v_pk_add_f32 v[10:11], v[10:11], v[26:27]
	s_mov_b64 s[48:49], -1
	s_and_b64 vcc, exec, s[40:41]
	v_lshl_add_u64 v[20:21], v[18:19], 2, s[8:9]
	s_cbranch_vccnz .LBB0_463
	s_mov_b64 s[48:49], 0
	global_store_dwordx4 v[20:21], v[14:17], off
	global_store_dwordx4 v[20:21], v[10:13], off offset:16

.LBB0_465:
	v_lshlrev_b32_e32 v10, 16, v66
	v_and_b32_e32 v11, 0xffff0000, v66
	v_lshlrev_b32_e32 v12, 16, v67
	v_and_b32_e32 v13, 0xffff0000, v67
	v_lshlrev_b32_e32 v14, 16, v68
	v_and_b32_e32 v15, 0xffff0000, v68
	v_lshlrev_b32_e32 v16, 16, v69
	v_and_b32_e32 v17, 0xffff0000, v69
	v_pk_add_f32 v[8:9], v[8:9], v[12:13]
	v_pk_add_f32 v[6:7], v[6:7], v[10:11]
	v_pk_add_f32 v[4:5], v[4:5], v[16:17]
	v_pk_add_f32 v[2:3], v[2:3], v[14:15]
	s_and_b64 vcc, exec, s[40:41]
	s_mov_b64 s[40:41], -1
	s_cbranch_vccnz .LBB0_468
	global_store_dwordx4 v[20:21], v[6:9], off offset:512
	global_store_dwordx4 v[20:21], v[2:5], off offset:528
	s_cbranch_execz .LBB0_469
